# down-proj residual prefetch: row order rotated so the rows the epilogue reads first are fetched in the last 16 K-iterations
# baseline (speedup 1.0000x reference)
; #define PG8_STAGE(bufoff, gbase, voff) do { _Pragma("unroll") for (int _i = 0; _i < 2; ++_i) \
;         __builtin_amdgcn_global_load_lds((const unsigned*)((const char*)(gbase) + (voff)[_i]), (LAS unsigned*)(lds + (bufoff) + ldsw + _i * 8192), 16, 0, 0); } while (0)
; #define PG8_LDA(dst, b, h) do { _Pragma("unroll") for (int m = 0; m < 4; ++m) _Pragma("unroll") for (int k = 0; k < 2; ++k) dst[m][k] = *(const LAS bf16x8*)(lds + PG8_SA(b, h) + aoff + m * 2048 + k * 1024); } while (0)
; #define PG8_LDB(dst, b, h) do { _Pragma("unroll") for (int n = 0; n < 2; ++n) _Pragma("unroll") for (int k = 0; k < 2; ++k) dst[n][k] = *(const LAS bf16x8*)(lds + PG8_SB(b, h) + boff + n * 2048 + k * 1024); } while (0)
; #define PG8_MMA(ai, bj, At, Bt) do { __builtin_amdgcn_s_setprio(1); _Pragma("unroll") for (int m = 0; m < 4; ++m) _Pragma("unroll") for (int n = 0; n < 2; ++n) _Pragma("unroll") for (int k = 0; k < 2; ++k) \
;         acc[ai][bj][m][n] = __builtin_amdgcn_mfma_f32_16x16x32_bf16(Bt[n][k], At[m][k], acc[ai][bj][m][n], 0, 0, 0); __builtin_amdgcn_s_setprio(0); } while (0)
; #define PG8_WAIT_V(n) asm volatile("s_waitcnt vmcnt(" #n ")" ::: "memory")
; #define PG8_WAIT_L(n) asm volatile("s_waitcnt lgkmcnt(" #n ")" ::: "memory")
; #define PG8_BAR __builtin_amdgcn_s_barrier()
; #define PG8_SCHED __builtin_amdgcn_sched_barrier(0)
; template <class Epi, bool ALIGN_EPI>
; __device__ __forceinline__ void gemm_phase(LAS unsigned char* lds, const Gemm g, int G, int cid, const Epi& E) {
;     ...
;             PG8_LDB(B0, 0, 0); PG8_LDB(B1, 0, 1); PG8_SCHED; PG8_LDA(At, 0, 0); PG8_STAGE(PG8_SA(1, 1), a1 + hA, voffA);
;             PG8_WAIT_V(8); PG8_WAIT_L(0); PG8_BAR; PG8_MMA(0, 0, At, B0); PG8_MMA(0, 1, At, B1); PG8_BAR; PG8_SCHED;
;             PG8_LDA(At, 0, 1); PG8_STAGE(PG8_SB(0, 0), b2, voffB); PG8_STAGE(PG8_SB(0, 1), b2 + hB, voffB); PG8_STAGE(PG8_SA(0, 0), a2, voffA);
;             PG8_WAIT_V(8); PG8_WAIT_L(0); PG8_BAR; PG8_MMA(1, 0, At, B0); PG8_MMA(1, 1, At, B1); PG8_BAR; PG8_SCHED;
.LBB0_927:
	s_add_u32 s40, s48, 0x100
	s_addc_u32 s41, s49, 0
	s_add_i32 s6, 0, 0x10000
	s_cmpk_eq_i32 s79, 0x54
	s_cselect_b32 s53, s45, s41
	s_cselect_b32 s52, s44, s40
	s_cselect_b32 s51, s30, s78
	s_cselect_b32 s50, s76, s77
	s_add_i32 s86, 0, 0x14000
	v_add_u32_e32 v144, s6, v243
	v_add_u32_e32 v160, s86, v243
	ds_read_b128 v[128:131], v144
	ds_read_b128 v[132:135], v144 offset:1024
	ds_read_b128 v[140:143], v144 offset:2048
	ds_read_b128 v[144:147], v144 offset:3072
	ds_read_b128 v[148:151], v160
	ds_read_b128 v[152:155], v160 offset:1024
	ds_read_b128 v[156:159], v160 offset:2048
	ds_read_b128 v[160:163], v160 offset:3072
	v_lshl_add_u64 v[198:199], s[48:49], 0, v[210:211]
	s_add_i32 m0, s12, 0xc000
	ds_read_b128 v[164:167], v245
	ds_read_b128 v[168:171], v245 offset:1024
	ds_read_b128 v[172:175], v245 offset:2048
	ds_read_b128 v[176:179], v245 offset:3072
	ds_read_b128 v[180:183], v245 offset:4096
	ds_read_b128 v[184:187], v245 offset:5120
	ds_read_b128 v[188:191], v245 offset:6144
	ds_read_b128 v[214:217], v245 offset:7168
	global_load_lds_dwordx4 v[198:199], off
	v_lshl_add_u64 v[198:199], s[48:49], 0, v[212:213]
	s_add_i32 m0, s12, 0xe000
	s_nop 0
	global_load_lds_dwordx4 v[198:199], off
	s_add_i32 vcc_lo, s79, 10
	s_lshl_b32 vcc_lo, vcc_lo, 15
	s_and_b32 vcc_lo, vcc_lo, 0x1f0000
	s_lshl_b32 vcc_hi, s75, 21
	s_add_i32 vcc_lo, vcc_lo, vcc_hi
	s_lshl_b32 vcc_hi, s25, 3
	s_add_i32 vcc_lo, vcc_lo, vcc_hi
	s_lshl_b32 vcc_hi, s74, 10
	s_add_i32 vcc_lo, vcc_lo, vcc_hi
	s_add_u32 vcc_lo, s82, vcc_lo
	s_addc_u32 vcc_hi, s83, 0
	s_mov_b32 m0, 0x22c00
	s_nop 0
	global_load_lds_dwordx4 v226, vcc
	s_waitcnt vmcnt(9)
	s_waitcnt lgkmcnt(0)
	s_barrier
	s_setprio 1
	s_waitcnt lgkmcnt(0)
	v_mfma_f32_16x16x32_bf16 v[124:127], v[128:131], v[164:167], v[124:127]
	v_mfma_f32_16x16x32_bf16 v[120:123], v[140:143], v[164:167], v[120:123]
	v_mfma_f32_16x16x32_bf16 v[108:111], v[128:131], v[172:175], v[108:111]
	v_mfma_f32_16x16x32_bf16 v[104:107], v[140:143], v[172:175], v[104:107]
	v_mfma_f32_16x16x32_bf16 v[92:95], v[128:131], v[180:183], v[92:95]
	v_mfma_f32_16x16x32_bf16 v[88:91], v[140:143], v[180:183], v[88:91]
	v_mfma_f32_16x16x32_bf16 v[76:79], v[128:131], v[188:191], v[76:79]
	v_mfma_f32_16x16x32_bf16 v[72:75], v[140:143], v[188:191], v[72:75]
	v_mfma_f32_16x16x32_bf16 v[124:127], v[132:135], v[168:171], v[124:127]
	v_mfma_f32_16x16x32_bf16 v[120:123], v[144:147], v[168:171], v[120:123]
	v_mfma_f32_16x16x32_bf16 v[108:111], v[132:135], v[176:179], v[108:111]
	v_mfma_f32_16x16x32_bf16 v[104:107], v[144:147], v[176:179], v[104:107]
	v_mfma_f32_16x16x32_bf16 v[92:95], v[132:135], v[184:187], v[92:95]
	v_mfma_f32_16x16x32_bf16 v[88:91], v[144:147], v[184:187], v[88:91]
	v_mfma_f32_16x16x32_bf16 v[76:79], v[132:135], v[214:217], v[76:79]
	v_mfma_f32_16x16x32_bf16 v[72:75], v[144:147], v[214:217], v[72:75]
	s_setprio 0
	s_setprio 1
	v_mfma_f32_16x16x32_bf16 v[116:119], v[148:151], v[164:167], v[116:119]
	v_mfma_f32_16x16x32_bf16 v[112:115], v[156:159], v[164:167], v[112:115]
	v_mfma_f32_16x16x32_bf16 v[100:103], v[148:151], v[172:175], v[100:103]
	v_mfma_f32_16x16x32_bf16 v[96:99], v[156:159], v[172:175], v[96:99]
	v_mfma_f32_16x16x32_bf16 v[84:87], v[148:151], v[180:183], v[84:87]
	v_mfma_f32_16x16x32_bf16 v[80:83], v[156:159], v[180:183], v[80:83]
	v_mfma_f32_16x16x32_bf16 v[68:71], v[148:151], v[188:191], v[68:71]
	v_mfma_f32_16x16x32_bf16 v[64:67], v[156:159], v[188:191], v[64:67]
	v_mfma_f32_16x16x32_bf16 v[116:119], v[152:155], v[168:171], v[116:119]
	v_mfma_f32_16x16x32_bf16 v[112:115], v[160:163], v[168:171], v[112:115]
	v_mfma_f32_16x16x32_bf16 v[100:103], v[152:155], v[176:179], v[100:103]
	v_mfma_f32_16x16x32_bf16 v[96:99], v[160:163], v[176:179], v[96:99]
	v_mfma_f32_16x16x32_bf16 v[84:87], v[152:155], v[184:187], v[84:87]
	v_mfma_f32_16x16x32_bf16 v[80:83], v[160:163], v[184:187], v[80:83]
	v_mfma_f32_16x16x32_bf16 v[68:71], v[152:155], v[214:217], v[68:71]
	v_mfma_f32_16x16x32_bf16 v[64:67], v[160:163], v[214:217], v[64:67]
	s_setprio 0
	s_barrier
	s_add_i32 s6, s6, s25
	v_lshl_add_u64 v[198:199], s[50:51], 0, v[138:139]
	s_mov_b32 m0, s6
	ds_read_b128 v[164:167], v245 offset:16384
	ds_read_b128 v[168:171], v245 offset:17408
	ds_read_b128 v[172:175], v245 offset:18432
	ds_read_b128 v[176:179], v245 offset:19456
	ds_read_b128 v[180:183], v245 offset:20480
	ds_read_b128 v[184:187], v245 offset:21504
	ds_read_b128 v[188:191], v245 offset:22528
	ds_read_b128 v[214:217], v245 offset:23552
	global_load_lds_dwordx4 v[198:199], off
	s_add_i32 m0, s6, 0x2000
	s_add_u32 s6, s50, 0x2000
	v_lshl_add_u64 v[198:199], s[50:51], 0, v[136:137]
	s_addc_u32 s7, s51, 0
	s_add_i32 s48, s86, s25
	global_load_lds_dwordx4 v[198:199], off
	v_lshl_add_u64 v[198:199], s[6:7], 0, v[138:139]
	s_mov_b32 m0, s48
	v_lshl_add_u64 v[200:201], s[52:53], 0, v[206:207]
	global_load_lds_dwordx4 v[198:199], off
	v_lshl_add_u64 v[198:199], s[6:7], 0, v[136:137]
	s_add_i32 m0, s48, 0x2000
	s_nop 0
	global_load_lds_dwordx4 v[198:199], off
	v_lshl_add_u64 v[198:199], s[52:53], 0, v[208:209]
	s_mov_b32 m0, s12
	s_nop 0
	global_load_lds_dwordx4 v[198:199], off
	s_mov_b32 m0, s13
	s_nop 0
	global_load_lds_dwordx4 v[200:201], off
	s_waitcnt vmcnt(9)
	s_waitcnt lgkmcnt(0)
	s_barrier
; #define PG8_STAGE(bufoff, gbase, voff) do { _Pragma("unroll") for (int _i = 0; _i < 2; ++_i) \
;         __builtin_amdgcn_global_load_lds((const unsigned*)((const char*)(gbase) + (voff)[_i]), (LAS unsigned*)(lds + (bufoff) + ldsw + _i * 8192), 16, 0, 0); } while (0)
; #define PG8_LDA(dst, b, h) do { _Pragma("unroll") for (int m = 0; m < 4; ++m) _Pragma("unroll") for (int k = 0; k < 2; ++k) dst[m][k] = *(const LAS bf16x8*)(lds + PG8_SA(b, h) + aoff + m * 2048 + k * 1024); } while (0)
; #define PG8_LDB(dst, b, h) do { _Pragma("unroll") for (int n = 0; n < 2; ++n) _Pragma("unroll") for (int k = 0; k < 2; ++k) dst[n][k] = *(const LAS bf16x8*)(lds + PG8_SB(b, h) + boff + n * 2048 + k * 1024); } while (0)
; #define PG8_MMA(ai, bj, At, Bt) do { __builtin_amdgcn_s_setprio(1); _Pragma("unroll") for (int m = 0; m < 4; ++m) _Pragma("unroll") for (int n = 0; n < 2; ++n) _Pragma("unroll") for (int k = 0; k < 2; ++k) \
;         acc[ai][bj][m][n] = __builtin_amdgcn_mfma_f32_16x16x32_bf16(Bt[n][k], At[m][k], acc[ai][bj][m][n], 0, 0, 0); __builtin_amdgcn_s_setprio(0); } while (0)
; #define PG8_WAIT_V(n) asm volatile("s_waitcnt vmcnt(" #n ")" ::: "memory")
; #define PG8_WAIT_L(n) asm volatile("s_waitcnt lgkmcnt(" #n ")" ::: "memory")
; #define PG8_BAR __builtin_amdgcn_s_barrier()
; #define PG8_SCHED __builtin_amdgcn_sched_barrier(0)
; template <class Epi, bool ALIGN_EPI>
; __device__ __forceinline__ void gemm_phase(LAS unsigned char* lds, const Gemm g, int G, int cid, const Epi& E) {
;     ...
;             PG8_WAIT_V(8); PG8_WAIT_L(0); PG8_BAR; PG8_MMA(1, 0, At, B0); PG8_MMA(1, 1, At, B1); PG8_BAR; PG8_SCHED;
;             PG8_LDB(B0, 1, 0); PG8_LDB(B1, 1, 1); PG8_SCHED; PG8_LDA(At, 1, 0); PG8_STAGE(PG8_SA(0, 1), a2 + hA, voffA);
;             PG8_WAIT_V(8); PG8_WAIT_L(0); PG8_BAR; PG8_MMA(0, 0, At, B0); PG8_MMA(0, 1, At, B1); PG8_BAR; PG8_SCHED;
;             PG8_LDA(At, 1, 1); PG8_STAGE(PG8_SB(1, 0), b3, voffB); PG8_STAGE(PG8_SB(1, 1), b3 + hB, voffB); PG8_STAGE(PG8_SA(1, 0), a3, voffA);
	s_setprio 1
	s_waitcnt lgkmcnt(0)
	v_mfma_f32_16x16x32_bf16 v[60:63], v[128:131], v[164:167], v[60:63]
	v_mfma_f32_16x16x32_bf16 v[56:59], v[140:143], v[164:167], v[56:59]
	v_mfma_f32_16x16x32_bf16 v[44:47], v[128:131], v[172:175], v[44:47]
	v_mfma_f32_16x16x32_bf16 v[40:43], v[140:143], v[172:175], v[40:43]
	v_mfma_f32_16x16x32_bf16 v[28:31], v[128:131], v[180:183], v[28:31]
	v_mfma_f32_16x16x32_bf16 v[24:27], v[140:143], v[180:183], v[24:27]
	v_mfma_f32_16x16x32_bf16 v[12:15], v[128:131], v[188:191], v[12:15]
	v_mfma_f32_16x16x32_bf16 v[8:11], v[140:143], v[188:191], v[8:11]
	v_mfma_f32_16x16x32_bf16 v[60:63], v[132:135], v[168:171], v[60:63]
	v_mfma_f32_16x16x32_bf16 v[56:59], v[144:147], v[168:171], v[56:59]
	v_mfma_f32_16x16x32_bf16 v[44:47], v[132:135], v[176:179], v[44:47]
	v_mfma_f32_16x16x32_bf16 v[40:43], v[144:147], v[176:179], v[40:43]
	v_mfma_f32_16x16x32_bf16 v[28:31], v[132:135], v[184:187], v[28:31]
	v_mfma_f32_16x16x32_bf16 v[24:27], v[144:147], v[184:187], v[24:27]
	v_mfma_f32_16x16x32_bf16 v[12:15], v[132:135], v[214:217], v[12:15]
	v_mfma_f32_16x16x32_bf16 v[8:11], v[144:147], v[214:217], v[8:11]
	s_setprio 0
	s_setprio 1
	v_mfma_f32_16x16x32_bf16 v[52:55], v[148:151], v[164:167], v[52:55]
	v_mfma_f32_16x16x32_bf16 v[48:51], v[156:159], v[164:167], v[48:51]
	v_mfma_f32_16x16x32_bf16 v[36:39], v[148:151], v[172:175], v[36:39]
	v_mfma_f32_16x16x32_bf16 v[32:35], v[156:159], v[172:175], v[32:35]
	v_mfma_f32_16x16x32_bf16 v[20:23], v[148:151], v[180:183], v[20:23]
	v_mfma_f32_16x16x32_bf16 v[16:19], v[156:159], v[180:183], v[16:19]
	v_mfma_f32_16x16x32_bf16 v[4:7], v[148:151], v[188:191], v[4:7]
	v_mfma_f32_16x16x32_bf16 v[0:3], v[156:159], v[188:191], v[0:3]
	v_mfma_f32_16x16x32_bf16 v[52:55], v[152:155], v[168:171], v[52:55]
	v_mfma_f32_16x16x32_bf16 v[48:51], v[160:163], v[168:171], v[48:51]
	v_mfma_f32_16x16x32_bf16 v[36:39], v[152:155], v[176:179], v[36:39]
	v_mfma_f32_16x16x32_bf16 v[32:35], v[160:163], v[176:179], v[32:35]
	v_mfma_f32_16x16x32_bf16 v[20:23], v[152:155], v[184:187], v[20:23]
	v_mfma_f32_16x16x32_bf16 v[16:19], v[160:163], v[184:187], v[16:19]
	v_mfma_f32_16x16x32_bf16 v[4:7], v[152:155], v[214:217], v[4:7]
	v_mfma_f32_16x16x32_bf16 v[0:3], v[160:163], v[214:217], v[0:3]
	s_setprio 0
	s_barrier
	s_add_i32 s48, 0, 0x18000
	s_add_i32 s49, 0, 0x1c000
	v_add_u32_e32 v144, s48, v243
	v_add_u32_e32 v160, s49, v243
	ds_read_b128 v[128:131], v144
	ds_read_b128 v[132:135], v144 offset:1024
	ds_read_b128 v[140:143], v144 offset:2048
	ds_read_b128 v[144:147], v144 offset:3072
	ds_read_b128 v[148:151], v160
	ds_read_b128 v[152:155], v160 offset:1024
	ds_read_b128 v[156:159], v160 offset:2048
	ds_read_b128 v[160:163], v160 offset:3072
	s_add_u32 s6, s52, 0x160000
	s_addc_u32 s7, s53, 0
	s_mov_b32 m0, s54
	v_lshl_add_u64 v[218:219], s[6:7], 0, v[208:209]
	ds_read_b128 v[164:167], v245 offset:32768
	ds_read_b128 v[168:171], v245 offset:33792
	ds_read_b128 v[172:175], v245 offset:34816
	ds_read_b128 v[176:179], v245 offset:35840
	ds_read_b128 v[180:183], v245 offset:36864
	ds_read_b128 v[184:187], v245 offset:37888
	ds_read_b128 v[188:191], v245 offset:38912
	ds_read_b128 v[214:217], v245 offset:39936
	global_load_lds_dwordx4 v[218:219], off
	v_lshl_add_u64 v[218:219], s[6:7], 0, v[206:207]
	s_mov_b32 m0, s55
	s_nop 0
	global_load_lds_dwordx4 v[218:219], off
	s_waitcnt vmcnt(8)
	s_waitcnt lgkmcnt(0)
	s_barrier
	s_setprio 1
	s_waitcnt lgkmcnt(0)
	v_mfma_f32_16x16x32_bf16 v[124:127], v[128:131], v[164:167], v[124:127]
	v_mfma_f32_16x16x32_bf16 v[120:123], v[140:143], v[164:167], v[120:123]
	v_mfma_f32_16x16x32_bf16 v[108:111], v[128:131], v[172:175], v[108:111]
	v_mfma_f32_16x16x32_bf16 v[104:107], v[140:143], v[172:175], v[104:107]
	v_mfma_f32_16x16x32_bf16 v[92:95], v[128:131], v[180:183], v[92:95]
	v_mfma_f32_16x16x32_bf16 v[88:91], v[140:143], v[180:183], v[88:91]
	v_mfma_f32_16x16x32_bf16 v[76:79], v[128:131], v[188:191], v[76:79]
	v_mfma_f32_16x16x32_bf16 v[72:75], v[140:143], v[188:191], v[72:75]
	v_mfma_f32_16x16x32_bf16 v[124:127], v[132:135], v[168:171], v[124:127]
	v_mfma_f32_16x16x32_bf16 v[120:123], v[144:147], v[168:171], v[120:123]
	v_mfma_f32_16x16x32_bf16 v[108:111], v[132:135], v[176:179], v[108:111]
	v_mfma_f32_16x16x32_bf16 v[104:107], v[144:147], v[176:179], v[104:107]
	v_mfma_f32_16x16x32_bf16 v[92:95], v[132:135], v[184:187], v[92:95]
	v_mfma_f32_16x16x32_bf16 v[88:91], v[144:147], v[184:187], v[88:91]
	v_mfma_f32_16x16x32_bf16 v[76:79], v[132:135], v[214:217], v[76:79]
	v_mfma_f32_16x16x32_bf16 v[72:75], v[144:147], v[214:217], v[72:75]
	s_setprio 0
	s_setprio 1
	v_mfma_f32_16x16x32_bf16 v[116:119], v[148:151], v[164:167], v[116:119]
	v_mfma_f32_16x16x32_bf16 v[112:115], v[156:159], v[164:167], v[112:115]
	v_mfma_f32_16x16x32_bf16 v[100:103], v[148:151], v[172:175], v[100:103]
	v_mfma_f32_16x16x32_bf16 v[96:99], v[156:159], v[172:175], v[96:99]
	v_mfma_f32_16x16x32_bf16 v[84:87], v[148:151], v[180:183], v[84:87]
	v_mfma_f32_16x16x32_bf16 v[80:83], v[156:159], v[180:183], v[80:83]
	v_mfma_f32_16x16x32_bf16 v[68:71], v[148:151], v[188:191], v[68:71]
	v_mfma_f32_16x16x32_bf16 v[64:67], v[156:159], v[188:191], v[64:67]
	v_mfma_f32_16x16x32_bf16 v[116:119], v[152:155], v[168:171], v[116:119]
	v_mfma_f32_16x16x32_bf16 v[112:115], v[160:163], v[168:171], v[112:115]
	v_mfma_f32_16x16x32_bf16 v[100:103], v[152:155], v[176:179], v[100:103]
	v_mfma_f32_16x16x32_bf16 v[96:99], v[160:163], v[176:179], v[96:99]
	v_mfma_f32_16x16x32_bf16 v[84:87], v[152:155], v[184:187], v[84:87]
	v_mfma_f32_16x16x32_bf16 v[80:83], v[160:163], v[184:187], v[80:83]
	v_mfma_f32_16x16x32_bf16 v[68:71], v[152:155], v[214:217], v[68:71]
	v_mfma_f32_16x16x32_bf16 v[64:67], v[160:163], v[214:217], v[64:67]
	s_setprio 0
	s_barrier
; __device__ __forceinline__ unsigned cvt_pk_bf16(float lo, float hi) { unsigned r; asm volatile("v_cvt_pk_bf16_f32 %0, %1, %2" : "=v"(r) : "v"(lo), "v"(hi)); return r; }
; #define PG8_WAIT_V(n) asm volatile("s_waitcnt vmcnt(" #n ")" ::: "memory")
; #define PG8_WAIT_L(n) asm volatile("s_waitcnt lgkmcnt(" #n ")" ::: "memory")
; template <class Epi, bool ALIGN_EPI>
; __device__ __forceinline__ void gemm_phase(LAS unsigned char* lds, const Gemm g, int G, int cid, const Epi& E) {
;     ...
;             PG8_LDA(At, 1, 1); PG8_STAGE(PG8_SB(1, 0), b3, voffB); PG8_STAGE(PG8_SB(1, 1), b3 + hB, voffB); PG8_STAGE(PG8_SA(1, 0), a3, voffA);
;             PG8_WAIT_V(8); PG8_WAIT_L(0); PG8_BAR; PG8_MMA(1, 0, At, B0); PG8_MMA(1, 1, At, B1); PG8_BAR; PG8_SCHED;
;         }
;     __device__ __forceinline__ void operator()(const f32x4 (&acc)[2][2][4][2], const Unit& u, int wr, int wc, int fr, int fq, const LAS float*) const {
;     ...
;         for (int am = 0; am < NB; ++am) { const int ai = am / (NB / 2), m0 = (am % (NB / 2)) * MB;
;             f32x4 xo[4][2][2];
; #pragma unroll
;             for (int m = m0; m < m0 + MB; ++m) { const float* xr = Xs + (size_t)(row0 + ai * HALF + m * 16) * DM + col0;
; #pragma unroll
;                 for (int bj = 0; bj < 2; ++bj) { xo[m][bj][0] = *(const f32x4*)(xr + bj * HALF); xo[m][bj][1] = *(const f32x4*)(xr + bj * HALF + 4); } }
; #pragma unroll
;             for (int m = m0; m < m0 + MB; ++m) { const int row = row0 + ai * HALF + m * 16; float ss = 0.f;
;                 float* xr = X + (size_t)row * DM + col0; bf16_t* xb = XB + (size_t)row * ALD + col0;
; #pragma unroll
;                 for (int bj = 0; bj < 2; ++bj) { f32x4 x0 = xo[m][bj][0], x1 = xo[m][bj][1];
;                     if (HB) { x0 += (acc[ai][bj][m][0] + bv[bj][0]) * sv[bj][0]; x1 += (acc[ai][bj][m][1] + bv[bj][1]) * sv[bj][1]; } else { x0 += acc[ai][bj][m][0]; x1 += acc[ai][bj][m][1]; }
;                     *(f32x4*)(xr + bj * HALF) = x0; *(f32x4*)(xr + bj * HALF + 4) = x1;
;                     ss += (x0[0] * x0[0] + x0[1] * x0[1]) + (x0[2] * x0[2] + x0[3] * x0[3]) + (x1[0] * x1[0] + x1[1] * x1[1]) + (x1[2] * x1[2] + x1[3] * x1[3]);
;                     u32x4 w; w.x = cvt_pk_bf16(x0[0], x0[1]); w.y = cvt_pk_bf16(x0[2], x0[3]); w.z = cvt_pk_bf16(x1[0], x1[1]); w.w = cvt_pk_bf16(x1[2], x1[3]);
;                     if (feeds) *(u32x4*)(xb + bj * HALF) = w; }
	s_add_u32 s6, s50, 0x40000
	s_addc_u32 s7, s51, 0
	s_add_i32 s48, s48, s25
	v_lshl_add_u64 v[218:219], s[6:7], 0, v[138:139]
	s_mov_b32 m0, s48
	ds_read_b128 v[164:167], v245 offset:49152
	ds_read_b128 v[168:171], v245 offset:50176
	ds_read_b128 v[172:175], v245 offset:51200
	ds_read_b128 v[176:179], v245 offset:52224
	ds_read_b128 v[180:183], v245 offset:53248
	ds_read_b128 v[184:187], v245 offset:54272
	ds_read_b128 v[188:191], v245 offset:55296
	ds_read_b128 v[214:217], v245 offset:56320
	global_load_lds_dwordx4 v[218:219], off
	s_add_i32 m0, s48, 0x2000
	v_lshl_add_u64 v[218:219], s[6:7], 0, v[136:137]
	s_add_u32 s6, s50, 0x42000
	s_addc_u32 s7, s51, 0
	s_add_i32 s48, s49, s25
	global_load_lds_dwordx4 v[218:219], off
	v_lshl_add_u64 v[218:219], s[6:7], 0, v[138:139]
	s_mov_b32 m0, s48
	v_lshl_add_u64 v[198:199], v[198:199], 0, s[36:37]
	global_load_lds_dwordx4 v[218:219], off
	v_lshl_add_u64 v[218:219], s[6:7], 0, v[136:137]
	s_add_i32 m0, s48, 0x2000
	s_nop 0
	global_load_lds_dwordx4 v[218:219], off
	s_mov_b32 m0, s57
	s_nop 0
	global_load_lds_dwordx4 v[198:199], off
	v_lshl_add_u64 v[198:199], v[200:201], 0, s[36:37]
	s_mov_b32 m0, s58
	s_nop 0
	global_load_lds_dwordx4 v[198:199], off
	s_waitcnt vmcnt(8)
	s_waitcnt lgkmcnt(0)
	s_barrier
	s_setprio 1
	s_waitcnt lgkmcnt(0)
	v_mfma_f32_16x16x32_bf16 v[60:63], v[128:131], v[164:167], v[60:63]
	v_mfma_f32_16x16x32_bf16 v[56:59], v[140:143], v[164:167], v[56:59]
	v_mfma_f32_16x16x32_bf16 v[44:47], v[128:131], v[172:175], v[44:47]
	v_mfma_f32_16x16x32_bf16 v[40:43], v[140:143], v[172:175], v[40:43]
	v_mfma_f32_16x16x32_bf16 v[28:31], v[128:131], v[180:183], v[28:31]
	v_mfma_f32_16x16x32_bf16 v[24:27], v[140:143], v[180:183], v[24:27]
	v_mfma_f32_16x16x32_bf16 v[12:15], v[128:131], v[188:191], v[12:15]
	v_mfma_f32_16x16x32_bf16 v[8:11], v[140:143], v[188:191], v[8:11]
	v_mfma_f32_16x16x32_bf16 v[60:63], v[132:135], v[168:171], v[60:63]
	v_mfma_f32_16x16x32_bf16 v[56:59], v[144:147], v[168:171], v[56:59]
	v_mfma_f32_16x16x32_bf16 v[44:47], v[132:135], v[176:179], v[44:47]
	v_mfma_f32_16x16x32_bf16 v[40:43], v[144:147], v[176:179], v[40:43]
	v_mfma_f32_16x16x32_bf16 v[28:31], v[132:135], v[184:187], v[28:31]
	v_mfma_f32_16x16x32_bf16 v[24:27], v[144:147], v[184:187], v[24:27]
	v_mfma_f32_16x16x32_bf16 v[12:15], v[132:135], v[214:217], v[12:15]
	v_mfma_f32_16x16x32_bf16 v[8:11], v[144:147], v[214:217], v[8:11]
	s_setprio 0
	s_setprio 1
	v_mfma_f32_16x16x32_bf16 v[52:55], v[148:151], v[164:167], v[52:55]
	v_mfma_f32_16x16x32_bf16 v[48:51], v[156:159], v[164:167], v[48:51]
	v_mfma_f32_16x16x32_bf16 v[36:39], v[148:151], v[172:175], v[36:39]
	v_mfma_f32_16x16x32_bf16 v[32:35], v[156:159], v[172:175], v[32:35]
	v_mfma_f32_16x16x32_bf16 v[20:23], v[148:151], v[180:183], v[20:23]
	v_mfma_f32_16x16x32_bf16 v[16:19], v[156:159], v[180:183], v[16:19]
	v_mfma_f32_16x16x32_bf16 v[4:7], v[148:151], v[188:191], v[4:7]
	v_mfma_f32_16x16x32_bf16 v[0:3], v[156:159], v[188:191], v[0:3]
	v_mfma_f32_16x16x32_bf16 v[52:55], v[152:155], v[168:171], v[52:55]
	v_mfma_f32_16x16x32_bf16 v[48:51], v[160:163], v[168:171], v[48:51]
	v_mfma_f32_16x16x32_bf16 v[36:39], v[152:155], v[176:179], v[36:39]
	v_mfma_f32_16x16x32_bf16 v[32:35], v[160:163], v[176:179], v[32:35]
	v_mfma_f32_16x16x32_bf16 v[20:23], v[152:155], v[184:187], v[20:23]
	v_mfma_f32_16x16x32_bf16 v[16:19], v[160:163], v[184:187], v[16:19]
	v_mfma_f32_16x16x32_bf16 v[4:7], v[152:155], v[214:217], v[4:7]
	v_mfma_f32_16x16x32_bf16 v[0:3], v[160:163], v[214:217], v[0:3]
	s_setprio 0
	s_barrier
	s_add_i32 s79, s79, 2
	s_add_u32 s77, s77, 0x80000
	s_addc_u32 s78, s78, 0
	s_cmpk_gt_u32 s79, 0x55
	s_mov_b64 s[48:49], s[40:41]
	s_cbranch_scc0 .LBB0_927
	v_lshl_or_b32 v214, s74, 8, v244
	v_lshl_add_u32 v216, s75, 8, v197
	v_ashrrev_i32_e32 v215, 31, v214
	v_lshlrev_b64 v[198:199], 2, v[214:215]
	v_ashrrev_i32_e32 v217, 31, v216
	v_or_b32_e32 v226, 16, v216
	v_lshl_add_u64 v[218:219], s[82:83], 0, v[198:199]
	v_lshlrev_b64 v[200:201], 13, v[216:217]
	v_ashrrev_i32_e32 v227, 31, v226
	v_or_b32_e32 v222, 32, v216
	v_or_b32_e32 v220, 48, v216
	v_lshl_add_u64 v[128:129], v[218:219], 0, v[200:201]
	v_lshlrev_b64 v[230:231], 13, v[226:227]
	v_ashrrev_i32_e32 v223, 31, v222
	v_ashrrev_i32_e32 v221, 31, v220
	global_load_dwordx4 v[188:191], v[128:129], off offset:16
	global_load_dwordx4 v[246:249], v[128:129], off
	global_load_dwordx4 v[180:183], v[128:129], off offset:528
	global_load_dwordx4 v[184:187], v[128:129], off offset:512
	v_lshl_add_u64 v[128:129], v[218:219], 0, v[230:231]
	v_lshlrev_b64 v[228:229], 13, v[222:223]
	v_lshlrev_b64 v[224:225], 13, v[220:221]
	global_load_dwordx4 v[172:175], v[128:129], off offset:16
	global_load_dwordx4 v[176:179], v[128:129], off
	global_load_dwordx4 v[164:167], v[128:129], off offset:528
	global_load_dwordx4 v[168:171], v[128:129], off offset:512
	v_lshl_add_u64 v[128:129], v[218:219], 0, v[228:229]
	v_lshl_add_u64 v[132:133], v[218:219], 0, v[224:225]
	global_load_dwordx4 v[156:159], v[128:129], off offset:16
	global_load_dwordx4 v[160:163], v[128:129], off
	global_load_dwordx4 v[148:151], v[128:129], off offset:528
	global_load_dwordx4 v[152:155], v[128:129], off offset:512
	global_load_dwordx4 v[140:143], v[132:133], off offset:16
	global_load_dwordx4 v[144:147], v[132:133], off
	s_nop 0
	global_load_dwordx4 v[128:131], v[132:133], off offset:528
	s_nop 0
	global_load_dwordx4 v[132:135], v[132:133], off offset:512
	v_lshl_add_u64 v[200:201], s[82:83], 0, v[200:201]
	v_lshl_add_u64 v[234:235], v[200:201], 0, v[198:199]
	v_mov_b64_e32 v[198:199], s[4:5]
	v_mad_i64_i32 v[198:199], s[6:7], v216, s66, v[198:199]
	v_lshl_add_u64 v[232:233], v[214:215], 1, v[198:199]
	s_and_b64 vcc, exec, s[28:29]
	s_waitcnt vmcnt(12)
	v_pk_add_f32 v[122:123], v[122:123], v[190:191]
	v_pk_add_f32 v[126:127], v[126:127], v[248:249]
	v_pk_add_f32 v[124:125], v[124:125], v[246:247]
	v_pk_add_f32 v[120:121], v[120:121], v[188:189]
	global_store_dwordx4 v[234:235], v[124:127], off
	global_store_dwordx4 v[234:235], v[120:123], off offset:16
	v_cvt_pk_bf16_f32 v188, v124, v125
	v_cvt_pk_bf16_f32 v189, v126, v127
	v_cvt_pk_bf16_f32 v190, v120, v121
	v_cvt_pk_bf16_f32 v191, v122, v123
	s_cbranch_vccz .LBB0_930
	global_store_dwordx4 v[232:233], v[188:191], off
